# ffup epilogues hand-written: same exp2 + IEEE-div math, software-pipelined; bf16 tile staged via wave-private LDS strip, 4 dwordx4 stores per wave instead of 32 short stores
# speedup vs baseline: 1.0129x; 1.0057x over previous
.LBB0_1034:
	v_lshl_or_b32 v115, v183, 3, v191
	v_lshrrev_b32_e32 v116, 6, v115
	v_and_b32_e32 v117, 63, v115
	v_lshlrev_b32_e32 v113, 11, v116
	v_add_u32_e32 v113, 0x10000, v113
	v_readfirstlane_b32 s100, v116
	v_and_b32_e32 v112, 31, v117
	v_lshl_add_u32 v112, v112, 1, v113
	v_lshrrev_b32_e32 v116, 5, v117
	v_lshl_add_u32 v112, v116, 8, v112
	v_lshl_add_u32 v113, v117, 4, v113
	v_lshrrev_b32_e32 v116, 2, v117
	v_mul_u32_u24_e32 v116, 0x1600, v116
	v_and_b32_e32 v114, 3, v117
	v_lshl_add_u32 v114, v114, 4, v116
	s_lshr_b32 s101, s100, 1
	s_lshl_b32 s101, s101, 6
	s_add_u32 s101, s101, s48
	s_mul_i32 s101, s101, 0x1600
	s_and_b32 s100, s100, 1
	s_lshl_b32 s100, s100, 6
	s_add_u32 s100, s100, s49
	s_add_u32 s101, s101, s100
	s_add_u32 s98, s90, 0x3971900
	s_addc_u32 s99, s91, 0
	s_add_u32 s98, s98, s101
	s_addc_u32 s99, s99, 0
	v_mul_f32_e32 v64, 0xbfb8aa3b, v48
	v_mul_f32_e32 v70, 0xbfb8aa3b, v49
	v_mul_f32_e32 v76, 0xbfb8aa3b, v50
	v_mul_f32_e32 v82, 0xbfb8aa3b, v51
	v_exp_f32_e32 v64, v64
	v_exp_f32_e32 v70, v70
	v_exp_f32_e32 v76, v76
	v_exp_f32_e32 v82, v82
	v_add_f32_e32 v64, 1.0, v64
	v_add_f32_e32 v70, 1.0, v70
	v_add_f32_e32 v76, 1.0, v76
	v_add_f32_e32 v82, 1.0, v82
	v_div_scale_f32 v65, s[2:3], v64, v64, 1.0
	v_div_scale_f32 v71, s[2:3], v70, v70, 1.0
	v_div_scale_f32 v77, s[2:3], v76, v76, 1.0
	v_div_scale_f32 v83, s[2:3], v82, v82, 1.0
	v_rcp_f32_e32 v66, v65
	v_rcp_f32_e32 v72, v71
	v_rcp_f32_e32 v78, v77
	v_rcp_f32_e32 v84, v83
	v_fma_f32 v69, -v65, v66, 1.0
	v_fma_f32 v75, -v71, v72, 1.0
	v_fma_f32 v81, -v77, v78, 1.0
	v_fma_f32 v87, -v83, v84, 1.0
	v_fmac_f32_e32 v66, v69, v66
	v_fmac_f32_e32 v72, v75, v72
	v_fmac_f32_e32 v78, v81, v78
	v_fmac_f32_e32 v84, v87, v84
	v_div_scale_f32 v67, vcc, 1.0, v64, 1.0
	v_mul_f32_e32 v88, 0xbfb8aa3b, v52
	v_mul_f32_e32 v68, v67, v66
	v_mul_f32_e32 v94, 0xbfb8aa3b, v53
	v_fma_f32 v69, -v65, v68, v67
	v_mul_f32_e32 v100, 0xbfb8aa3b, v54
	v_fmac_f32_e32 v68, v69, v66
	v_mul_f32_e32 v106, 0xbfb8aa3b, v55
	v_fma_f32 v65, -v65, v68, v67
	v_exp_f32_e32 v88, v88
	v_div_fmas_f32 v65, v65, v66, v68
	v_exp_f32_e32 v94, v94
	v_div_scale_f32 v73, vcc, 1.0, v70, 1.0
	v_exp_f32_e32 v100, v100
	v_mul_f32_e32 v74, v73, v72
	v_exp_f32_e32 v106, v106
	v_fma_f32 v75, -v71, v74, v73
	v_add_f32_e32 v88, 1.0, v88
	v_fmac_f32_e32 v74, v75, v72
	v_add_f32_e32 v94, 1.0, v94
	v_fma_f32 v71, -v71, v74, v73
	v_add_f32_e32 v100, 1.0, v100
	v_div_fmas_f32 v71, v71, v72, v74
	v_add_f32_e32 v106, 1.0, v106
	v_div_scale_f32 v79, vcc, 1.0, v76, 1.0
	v_div_scale_f32 v89, s[2:3], v88, v88, 1.0
	v_mul_f32_e32 v80, v79, v78
	v_div_scale_f32 v95, s[2:3], v94, v94, 1.0
	v_fma_f32 v81, -v77, v80, v79
	v_div_scale_f32 v101, s[2:3], v100, v100, 1.0
	v_fmac_f32_e32 v80, v81, v78
	v_div_scale_f32 v107, s[2:3], v106, v106, 1.0
	v_fma_f32 v77, -v77, v80, v79
	v_rcp_f32_e32 v90, v89
	v_div_fmas_f32 v77, v77, v78, v80
	v_rcp_f32_e32 v96, v95
	v_div_scale_f32 v85, vcc, 1.0, v82, 1.0
	v_rcp_f32_e32 v102, v101
	v_mul_f32_e32 v86, v85, v84
	v_rcp_f32_e32 v108, v107
	v_fma_f32 v87, -v83, v86, v85
	v_fma_f32 v93, -v89, v90, 1.0
	v_fmac_f32_e32 v86, v87, v84
	v_fma_f32 v99, -v95, v96, 1.0
	v_fma_f32 v83, -v83, v86, v85
	v_fma_f32 v105, -v101, v102, 1.0
	v_div_fmas_f32 v83, v83, v84, v86
	v_fma_f32 v111, -v107, v108, 1.0
	v_fmac_f32_e32 v90, v93, v90
	v_fmac_f32_e32 v96, v99, v96
	v_fmac_f32_e32 v102, v105, v102
	v_fmac_f32_e32 v108, v111, v108
	v_div_fixup_f32 v65, v65, v64, 1.0
	v_div_fixup_f32 v71, v71, v70, 1.0
	v_div_fixup_f32 v77, v77, v76, 1.0
	v_div_fixup_f32 v83, v83, v82, 1.0
	v_mul_f32_e32 v65, v48, v65
	v_mul_f32_e32 v71, v49, v71
	v_mul_f32_e32 v77, v50, v77
	v_mul_f32_e32 v83, v51, v83
	v_mul_f32_e32 v65, v32, v65
	v_mul_f32_e32 v71, v33, v71
	v_mul_f32_e32 v77, v34, v77
	v_mul_f32_e32 v83, v35, v83
	v_cvt_pk_bf16_f32 v65, v65, v65
	v_cvt_pk_bf16_f32 v71, v71, v71
	v_cvt_pk_bf16_f32 v77, v77, v77
	v_cvt_pk_bf16_f32 v83, v83, v83
	ds_write_b16 v112, v65
	ds_write_b16 v112, v71 offset:64
	ds_write_b16 v112, v77 offset:128
	ds_write_b16 v112, v83 offset:192
	v_div_scale_f32 v91, vcc, 1.0, v88, 1.0
	v_mul_f32_e32 v64, 0xbfb8aa3b, v56
	v_mul_f32_e32 v92, v91, v90
	v_mul_f32_e32 v70, 0xbfb8aa3b, v57
	v_fma_f32 v93, -v89, v92, v91
	v_mul_f32_e32 v76, 0xbfb8aa3b, v58
	v_fmac_f32_e32 v92, v93, v90
	v_mul_f32_e32 v82, 0xbfb8aa3b, v59
	v_fma_f32 v89, -v89, v92, v91
	v_exp_f32_e32 v64, v64
	v_div_fmas_f32 v89, v89, v90, v92
	v_exp_f32_e32 v70, v70
	v_div_scale_f32 v97, vcc, 1.0, v94, 1.0
	v_exp_f32_e32 v76, v76
	v_mul_f32_e32 v98, v97, v96
	v_exp_f32_e32 v82, v82
	v_fma_f32 v99, -v95, v98, v97
	v_add_f32_e32 v64, 1.0, v64
	v_fmac_f32_e32 v98, v99, v96
	v_add_f32_e32 v70, 1.0, v70
	v_fma_f32 v95, -v95, v98, v97
	v_add_f32_e32 v76, 1.0, v76
	v_div_fmas_f32 v95, v95, v96, v98
	v_add_f32_e32 v82, 1.0, v82
	v_div_scale_f32 v103, vcc, 1.0, v100, 1.0
	v_div_scale_f32 v65, s[2:3], v64, v64, 1.0
	v_mul_f32_e32 v104, v103, v102
	v_div_scale_f32 v71, s[2:3], v70, v70, 1.0
	v_fma_f32 v105, -v101, v104, v103
	v_div_scale_f32 v77, s[2:3], v76, v76, 1.0
	v_fmac_f32_e32 v104, v105, v102
	v_div_scale_f32 v83, s[2:3], v82, v82, 1.0
	v_fma_f32 v101, -v101, v104, v103
	v_rcp_f32_e32 v66, v65
	v_div_fmas_f32 v101, v101, v102, v104
	v_rcp_f32_e32 v72, v71
	v_div_scale_f32 v109, vcc, 1.0, v106, 1.0
	v_rcp_f32_e32 v78, v77
	v_mul_f32_e32 v110, v109, v108
	v_rcp_f32_e32 v84, v83
	v_fma_f32 v111, -v107, v110, v109
	v_fma_f32 v69, -v65, v66, 1.0
	v_fmac_f32_e32 v110, v111, v108
	v_fma_f32 v75, -v71, v72, 1.0
	v_fma_f32 v107, -v107, v110, v109
	v_fma_f32 v81, -v77, v78, 1.0
	v_div_fmas_f32 v107, v107, v108, v110
	v_fma_f32 v87, -v83, v84, 1.0
	v_fmac_f32_e32 v66, v69, v66
	v_fmac_f32_e32 v72, v75, v72
	v_fmac_f32_e32 v78, v81, v78
	v_fmac_f32_e32 v84, v87, v84
	v_div_fixup_f32 v89, v89, v88, 1.0
	v_div_fixup_f32 v95, v95, v94, 1.0
	v_div_fixup_f32 v101, v101, v100, 1.0
	v_div_fixup_f32 v107, v107, v106, 1.0
	v_mul_f32_e32 v89, v52, v89
	v_mul_f32_e32 v95, v53, v95
	v_mul_f32_e32 v101, v54, v101
	v_mul_f32_e32 v107, v55, v107
	v_mul_f32_e32 v89, v36, v89
	v_mul_f32_e32 v95, v37, v95
	v_mul_f32_e32 v101, v38, v101
	v_mul_f32_e32 v107, v39, v107
	v_cvt_pk_bf16_f32 v89, v89, v89
	v_cvt_pk_bf16_f32 v95, v95, v95
	v_cvt_pk_bf16_f32 v101, v101, v101
	v_cvt_pk_bf16_f32 v107, v107, v107
	ds_write_b16 v112, v89 offset:512
	ds_write_b16 v112, v95 offset:576
	ds_write_b16 v112, v101 offset:640
	ds_write_b16 v112, v107 offset:704
	v_div_scale_f32 v67, vcc, 1.0, v64, 1.0
	v_mul_f32_e32 v88, 0xbfb8aa3b, v60
	v_mul_f32_e32 v68, v67, v66
	v_mul_f32_e32 v94, 0xbfb8aa3b, v61
	v_fma_f32 v69, -v65, v68, v67
	v_mul_f32_e32 v100, 0xbfb8aa3b, v62
	v_fmac_f32_e32 v68, v69, v66
	v_mul_f32_e32 v106, 0xbfb8aa3b, v63
	v_fma_f32 v65, -v65, v68, v67
	v_exp_f32_e32 v88, v88
	v_div_fmas_f32 v65, v65, v66, v68
	v_exp_f32_e32 v94, v94
	v_div_scale_f32 v73, vcc, 1.0, v70, 1.0
	v_exp_f32_e32 v100, v100
	v_mul_f32_e32 v74, v73, v72
	v_exp_f32_e32 v106, v106
	v_fma_f32 v75, -v71, v74, v73
	v_add_f32_e32 v88, 1.0, v88
	v_fmac_f32_e32 v74, v75, v72
	v_add_f32_e32 v94, 1.0, v94
	v_fma_f32 v71, -v71, v74, v73
	v_add_f32_e32 v100, 1.0, v100
	v_div_fmas_f32 v71, v71, v72, v74
	v_add_f32_e32 v106, 1.0, v106
	v_div_scale_f32 v79, vcc, 1.0, v76, 1.0
	v_div_scale_f32 v89, s[2:3], v88, v88, 1.0
	v_mul_f32_e32 v80, v79, v78
	v_div_scale_f32 v95, s[2:3], v94, v94, 1.0
	v_fma_f32 v81, -v77, v80, v79
	v_div_scale_f32 v101, s[2:3], v100, v100, 1.0
	v_fmac_f32_e32 v80, v81, v78
	v_div_scale_f32 v107, s[2:3], v106, v106, 1.0
	v_fma_f32 v77, -v77, v80, v79
	v_rcp_f32_e32 v90, v89
	v_div_fmas_f32 v77, v77, v78, v80
	v_rcp_f32_e32 v96, v95
	v_div_scale_f32 v85, vcc, 1.0, v82, 1.0
	v_rcp_f32_e32 v102, v101
	v_mul_f32_e32 v86, v85, v84
	v_rcp_f32_e32 v108, v107
	v_fma_f32 v87, -v83, v86, v85
	v_fma_f32 v93, -v89, v90, 1.0
	v_fmac_f32_e32 v86, v87, v84
	v_fma_f32 v99, -v95, v96, 1.0
	v_fma_f32 v83, -v83, v86, v85
	v_fma_f32 v105, -v101, v102, 1.0
	v_div_fmas_f32 v83, v83, v84, v86
	v_fma_f32 v111, -v107, v108, 1.0
	v_fmac_f32_e32 v90, v93, v90
	v_fmac_f32_e32 v96, v99, v96
	v_fmac_f32_e32 v102, v105, v102
	v_fmac_f32_e32 v108, v111, v108
	v_div_fixup_f32 v65, v65, v64, 1.0
	v_div_fixup_f32 v71, v71, v70, 1.0
	v_div_fixup_f32 v77, v77, v76, 1.0
	v_div_fixup_f32 v83, v83, v82, 1.0
	v_mul_f32_e32 v65, v56, v65
	v_mul_f32_e32 v71, v57, v71
	v_mul_f32_e32 v77, v58, v77
	v_mul_f32_e32 v83, v59, v83
	v_mul_f32_e32 v65, v40, v65
	v_mul_f32_e32 v71, v41, v71
	v_mul_f32_e32 v77, v42, v77
	v_mul_f32_e32 v83, v43, v83
	v_cvt_pk_bf16_f32 v65, v65, v65
	v_cvt_pk_bf16_f32 v71, v71, v71
	v_cvt_pk_bf16_f32 v77, v77, v77
	v_cvt_pk_bf16_f32 v83, v83, v83
	ds_write_b16 v112, v65 offset:1024
	ds_write_b16 v112, v71 offset:1088
	ds_write_b16 v112, v77 offset:1152
	ds_write_b16 v112, v83 offset:1216
	v_div_scale_f32 v91, vcc, 1.0, v88, 1.0
	v_mul_f32_e32 v64, 0xbfb8aa3b, v16
	v_mul_f32_e32 v92, v91, v90
	v_mul_f32_e32 v70, 0xbfb8aa3b, v17
	v_fma_f32 v93, -v89, v92, v91
	v_mul_f32_e32 v76, 0xbfb8aa3b, v18
	v_fmac_f32_e32 v92, v93, v90
	v_mul_f32_e32 v82, 0xbfb8aa3b, v19
	v_fma_f32 v89, -v89, v92, v91
	v_exp_f32_e32 v64, v64
	v_div_fmas_f32 v89, v89, v90, v92
	v_exp_f32_e32 v70, v70
	v_div_scale_f32 v97, vcc, 1.0, v94, 1.0
	v_exp_f32_e32 v76, v76
	v_mul_f32_e32 v98, v97, v96
	v_exp_f32_e32 v82, v82
	v_fma_f32 v99, -v95, v98, v97
	v_add_f32_e32 v64, 1.0, v64
	v_fmac_f32_e32 v98, v99, v96
	v_add_f32_e32 v70, 1.0, v70
	v_fma_f32 v95, -v95, v98, v97
	v_add_f32_e32 v76, 1.0, v76
	v_div_fmas_f32 v95, v95, v96, v98
	v_add_f32_e32 v82, 1.0, v82
	v_div_scale_f32 v103, vcc, 1.0, v100, 1.0
	v_div_scale_f32 v65, s[2:3], v64, v64, 1.0
	v_mul_f32_e32 v104, v103, v102
	v_div_scale_f32 v71, s[2:3], v70, v70, 1.0
	v_fma_f32 v105, -v101, v104, v103
	v_div_scale_f32 v77, s[2:3], v76, v76, 1.0
	v_fmac_f32_e32 v104, v105, v102
	v_div_scale_f32 v83, s[2:3], v82, v82, 1.0
	v_fma_f32 v101, -v101, v104, v103
	v_rcp_f32_e32 v66, v65
	v_div_fmas_f32 v101, v101, v102, v104
	v_rcp_f32_e32 v72, v71
	v_div_scale_f32 v109, vcc, 1.0, v106, 1.0
	v_rcp_f32_e32 v78, v77
	v_mul_f32_e32 v110, v109, v108
	v_rcp_f32_e32 v84, v83
	v_fma_f32 v111, -v107, v110, v109
	v_fma_f32 v69, -v65, v66, 1.0
	v_fmac_f32_e32 v110, v111, v108
	v_fma_f32 v75, -v71, v72, 1.0
	v_fma_f32 v107, -v107, v110, v109
	v_fma_f32 v81, -v77, v78, 1.0
	v_div_fmas_f32 v107, v107, v108, v110
	v_fma_f32 v87, -v83, v84, 1.0
	v_fmac_f32_e32 v66, v69, v66
	v_fmac_f32_e32 v72, v75, v72
	v_fmac_f32_e32 v78, v81, v78
	v_fmac_f32_e32 v84, v87, v84
	v_div_fixup_f32 v89, v89, v88, 1.0
	v_div_fixup_f32 v95, v95, v94, 1.0
	v_div_fixup_f32 v101, v101, v100, 1.0
	v_div_fixup_f32 v107, v107, v106, 1.0
	v_mul_f32_e32 v89, v60, v89
	v_mul_f32_e32 v95, v61, v95
	v_mul_f32_e32 v101, v62, v101
	v_mul_f32_e32 v107, v63, v107
	v_mul_f32_e32 v89, v44, v89
	v_mul_f32_e32 v95, v45, v95
	v_mul_f32_e32 v101, v46, v101
	v_mul_f32_e32 v107, v47, v107
	v_cvt_pk_bf16_f32 v89, v89, v89
	v_cvt_pk_bf16_f32 v95, v95, v95
	v_cvt_pk_bf16_f32 v101, v101, v101
	v_cvt_pk_bf16_f32 v107, v107, v107
	ds_write_b16 v112, v89 offset:1536
	ds_write_b16 v112, v95 offset:1600
	ds_write_b16 v112, v101 offset:1664
	ds_write_b16 v112, v107 offset:1728
	ds_read_b128 v[120:123], v113
	ds_read_b128 v[124:127], v113 offset:1024
	v_div_scale_f32 v67, vcc, 1.0, v64, 1.0
	v_mul_f32_e32 v88, 0xbfb8aa3b, v20
	v_mul_f32_e32 v68, v67, v66
	v_mul_f32_e32 v94, 0xbfb8aa3b, v21
	v_fma_f32 v69, -v65, v68, v67
	v_mul_f32_e32 v100, 0xbfb8aa3b, v22
	v_fmac_f32_e32 v68, v69, v66
	v_mul_f32_e32 v106, 0xbfb8aa3b, v23
	v_fma_f32 v65, -v65, v68, v67
	v_exp_f32_e32 v88, v88
	v_div_fmas_f32 v65, v65, v66, v68
	v_exp_f32_e32 v94, v94
	v_div_scale_f32 v73, vcc, 1.0, v70, 1.0
	v_exp_f32_e32 v100, v100
	v_mul_f32_e32 v74, v73, v72
	v_exp_f32_e32 v106, v106
	v_fma_f32 v75, -v71, v74, v73
	v_add_f32_e32 v88, 1.0, v88
	v_fmac_f32_e32 v74, v75, v72
	v_add_f32_e32 v94, 1.0, v94
	v_fma_f32 v71, -v71, v74, v73
	v_add_f32_e32 v100, 1.0, v100
	v_div_fmas_f32 v71, v71, v72, v74
	v_add_f32_e32 v106, 1.0, v106
	v_div_scale_f32 v79, vcc, 1.0, v76, 1.0
	v_div_scale_f32 v89, s[2:3], v88, v88, 1.0
	v_mul_f32_e32 v80, v79, v78
	v_div_scale_f32 v95, s[2:3], v94, v94, 1.0
	v_fma_f32 v81, -v77, v80, v79
	v_div_scale_f32 v101, s[2:3], v100, v100, 1.0
	v_fmac_f32_e32 v80, v81, v78
	v_div_scale_f32 v107, s[2:3], v106, v106, 1.0
	v_fma_f32 v77, -v77, v80, v79
	v_rcp_f32_e32 v90, v89
	v_div_fmas_f32 v77, v77, v78, v80
	v_rcp_f32_e32 v96, v95
	v_div_scale_f32 v85, vcc, 1.0, v82, 1.0
	v_rcp_f32_e32 v102, v101
	v_mul_f32_e32 v86, v85, v84
	v_rcp_f32_e32 v108, v107
	v_fma_f32 v87, -v83, v86, v85
	v_fma_f32 v93, -v89, v90, 1.0
	v_fmac_f32_e32 v86, v87, v84
	v_fma_f32 v99, -v95, v96, 1.0
	v_fma_f32 v83, -v83, v86, v85
	v_fma_f32 v105, -v101, v102, 1.0
	v_div_fmas_f32 v83, v83, v84, v86
	v_fma_f32 v111, -v107, v108, 1.0
	v_fmac_f32_e32 v90, v93, v90
	v_fmac_f32_e32 v96, v99, v96
	v_fmac_f32_e32 v102, v105, v102
	v_fmac_f32_e32 v108, v111, v108
	s_waitcnt lgkmcnt(0)
	global_store_dwordx4 v114, v[120:123], s[98:99]
	s_add_u32 s98, s98, 0x16000
	s_addc_u32 s99, s99, 0
	global_store_dwordx4 v114, v[124:127], s[98:99]
	s_add_u32 s98, s98, 0x16000
	s_addc_u32 s99, s99, 0
	v_div_fixup_f32 v65, v65, v64, 1.0
	v_div_fixup_f32 v71, v71, v70, 1.0
	v_div_fixup_f32 v77, v77, v76, 1.0
	v_div_fixup_f32 v83, v83, v82, 1.0
	v_mul_f32_e32 v65, v16, v65
	v_mul_f32_e32 v71, v17, v71
	v_mul_f32_e32 v77, v18, v77
	v_mul_f32_e32 v83, v19, v83
	v_mul_f32_e32 v65, v0, v65
	v_mul_f32_e32 v71, v1, v71
	v_mul_f32_e32 v77, v2, v77
	v_mul_f32_e32 v83, v3, v83
	v_cvt_pk_bf16_f32 v65, v65, v65
	v_cvt_pk_bf16_f32 v71, v71, v71
	v_cvt_pk_bf16_f32 v77, v77, v77
	v_cvt_pk_bf16_f32 v83, v83, v83
	ds_write_b16 v112, v65
	ds_write_b16 v112, v71 offset:64
	ds_write_b16 v112, v77 offset:128
	ds_write_b16 v112, v83 offset:192
	v_div_scale_f32 v91, vcc, 1.0, v88, 1.0
	v_mul_f32_e32 v64, 0xbfb8aa3b, v24
	v_mul_f32_e32 v92, v91, v90
	v_mul_f32_e32 v70, 0xbfb8aa3b, v25
	v_fma_f32 v93, -v89, v92, v91
	v_mul_f32_e32 v76, 0xbfb8aa3b, v26
	v_fmac_f32_e32 v92, v93, v90
	v_mul_f32_e32 v82, 0xbfb8aa3b, v27
	v_fma_f32 v89, -v89, v92, v91
	v_exp_f32_e32 v64, v64
	v_div_fmas_f32 v89, v89, v90, v92
	v_exp_f32_e32 v70, v70
	v_div_scale_f32 v97, vcc, 1.0, v94, 1.0
	v_exp_f32_e32 v76, v76
	v_mul_f32_e32 v98, v97, v96
	v_exp_f32_e32 v82, v82
	v_fma_f32 v99, -v95, v98, v97
	v_add_f32_e32 v64, 1.0, v64
	v_fmac_f32_e32 v98, v99, v96
	v_add_f32_e32 v70, 1.0, v70
	v_fma_f32 v95, -v95, v98, v97
	v_add_f32_e32 v76, 1.0, v76
	v_div_fmas_f32 v95, v95, v96, v98
	v_add_f32_e32 v82, 1.0, v82
	v_div_scale_f32 v103, vcc, 1.0, v100, 1.0
	v_div_scale_f32 v65, s[2:3], v64, v64, 1.0
	v_mul_f32_e32 v104, v103, v102
	v_div_scale_f32 v71, s[2:3], v70, v70, 1.0
	v_fma_f32 v105, -v101, v104, v103
	v_div_scale_f32 v77, s[2:3], v76, v76, 1.0
	v_fmac_f32_e32 v104, v105, v102
	v_div_scale_f32 v83, s[2:3], v82, v82, 1.0
	v_fma_f32 v101, -v101, v104, v103
	v_rcp_f32_e32 v66, v65
	v_div_fmas_f32 v101, v101, v102, v104
	v_rcp_f32_e32 v72, v71
	v_div_scale_f32 v109, vcc, 1.0, v106, 1.0
	v_rcp_f32_e32 v78, v77
	v_mul_f32_e32 v110, v109, v108
	v_rcp_f32_e32 v84, v83
	v_fma_f32 v111, -v107, v110, v109
	v_fma_f32 v69, -v65, v66, 1.0
	v_fmac_f32_e32 v110, v111, v108
	v_fma_f32 v75, -v71, v72, 1.0
	v_fma_f32 v107, -v107, v110, v109
	v_fma_f32 v81, -v77, v78, 1.0
	v_div_fmas_f32 v107, v107, v108, v110
	v_fma_f32 v87, -v83, v84, 1.0
	v_fmac_f32_e32 v66, v69, v66
	v_fmac_f32_e32 v72, v75, v72
	v_fmac_f32_e32 v78, v81, v78
	v_fmac_f32_e32 v84, v87, v84
	v_div_fixup_f32 v89, v89, v88, 1.0
	v_div_fixup_f32 v95, v95, v94, 1.0
	v_div_fixup_f32 v101, v101, v100, 1.0
	v_div_fixup_f32 v107, v107, v106, 1.0
	v_mul_f32_e32 v89, v20, v89
	v_mul_f32_e32 v95, v21, v95
	v_mul_f32_e32 v101, v22, v101
	v_mul_f32_e32 v107, v23, v107
	v_mul_f32_e32 v89, v4, v89
	v_mul_f32_e32 v95, v5, v95
	v_mul_f32_e32 v101, v6, v101
	v_mul_f32_e32 v107, v7, v107
	v_cvt_pk_bf16_f32 v89, v89, v89
	v_cvt_pk_bf16_f32 v95, v95, v95
	v_cvt_pk_bf16_f32 v101, v101, v101
	v_cvt_pk_bf16_f32 v107, v107, v107
	ds_write_b16 v112, v89 offset:512
	ds_write_b16 v112, v95 offset:576
	ds_write_b16 v112, v101 offset:640
	ds_write_b16 v112, v107 offset:704
	v_div_scale_f32 v67, vcc, 1.0, v64, 1.0
	v_mul_f32_e32 v88, 0xbfb8aa3b, v28
	v_mul_f32_e32 v68, v67, v66
	v_mul_f32_e32 v94, 0xbfb8aa3b, v29
	v_fma_f32 v69, -v65, v68, v67
	v_mul_f32_e32 v100, 0xbfb8aa3b, v30
	v_fmac_f32_e32 v68, v69, v66
	v_mul_f32_e32 v106, 0xbfb8aa3b, v31
	v_fma_f32 v65, -v65, v68, v67
	v_exp_f32_e32 v88, v88
	v_div_fmas_f32 v65, v65, v66, v68
	v_exp_f32_e32 v94, v94
	v_div_scale_f32 v73, vcc, 1.0, v70, 1.0
	v_exp_f32_e32 v100, v100
	v_mul_f32_e32 v74, v73, v72
	v_exp_f32_e32 v106, v106
	v_fma_f32 v75, -v71, v74, v73
	v_add_f32_e32 v88, 1.0, v88
	v_fmac_f32_e32 v74, v75, v72
	v_add_f32_e32 v94, 1.0, v94
	v_fma_f32 v71, -v71, v74, v73
	v_add_f32_e32 v100, 1.0, v100
	v_div_fmas_f32 v71, v71, v72, v74
	v_add_f32_e32 v106, 1.0, v106
	v_div_scale_f32 v79, vcc, 1.0, v76, 1.0
	v_div_scale_f32 v89, s[2:3], v88, v88, 1.0
	v_mul_f32_e32 v80, v79, v78
	v_div_scale_f32 v95, s[2:3], v94, v94, 1.0
	v_fma_f32 v81, -v77, v80, v79
	v_div_scale_f32 v101, s[2:3], v100, v100, 1.0
	v_fmac_f32_e32 v80, v81, v78
	v_div_scale_f32 v107, s[2:3], v106, v106, 1.0
	v_fma_f32 v77, -v77, v80, v79
	v_rcp_f32_e32 v90, v89
	v_div_fmas_f32 v77, v77, v78, v80
	v_rcp_f32_e32 v96, v95
	v_div_scale_f32 v85, vcc, 1.0, v82, 1.0
	v_rcp_f32_e32 v102, v101
	v_mul_f32_e32 v86, v85, v84
	v_rcp_f32_e32 v108, v107
	v_fma_f32 v87, -v83, v86, v85
	v_fma_f32 v93, -v89, v90, 1.0
	v_fmac_f32_e32 v86, v87, v84
	v_fma_f32 v99, -v95, v96, 1.0
	v_fma_f32 v83, -v83, v86, v85
	v_fma_f32 v105, -v101, v102, 1.0
	v_div_fmas_f32 v83, v83, v84, v86
	v_fma_f32 v111, -v107, v108, 1.0
	v_fmac_f32_e32 v90, v93, v90
	v_fmac_f32_e32 v96, v99, v96
	v_fmac_f32_e32 v102, v105, v102
	v_fmac_f32_e32 v108, v111, v108
	v_div_fixup_f32 v65, v65, v64, 1.0
	v_div_fixup_f32 v71, v71, v70, 1.0
	v_div_fixup_f32 v77, v77, v76, 1.0
	v_div_fixup_f32 v83, v83, v82, 1.0
	v_mul_f32_e32 v65, v24, v65
	v_mul_f32_e32 v71, v25, v71
	v_mul_f32_e32 v77, v26, v77
	v_mul_f32_e32 v83, v27, v83
	v_mul_f32_e32 v65, v8, v65
	v_mul_f32_e32 v71, v9, v71
	v_mul_f32_e32 v77, v10, v77
	v_mul_f32_e32 v83, v11, v83
	v_cvt_pk_bf16_f32 v65, v65, v65
	v_cvt_pk_bf16_f32 v71, v71, v71
	v_cvt_pk_bf16_f32 v77, v77, v77
	v_cvt_pk_bf16_f32 v83, v83, v83
	ds_write_b16 v112, v65 offset:1024
	ds_write_b16 v112, v71 offset:1088
	ds_write_b16 v112, v77 offset:1152
	ds_write_b16 v112, v83 offset:1216
	v_div_scale_f32 v91, vcc, 1.0, v88, 1.0
	v_mul_f32_e32 v92, v91, v90
	v_fma_f32 v93, -v89, v92, v91
	v_fmac_f32_e32 v92, v93, v90
	v_fma_f32 v89, -v89, v92, v91
	v_div_fmas_f32 v89, v89, v90, v92
	v_div_scale_f32 v97, vcc, 1.0, v94, 1.0
	v_mul_f32_e32 v98, v97, v96
	v_fma_f32 v99, -v95, v98, v97
	v_fmac_f32_e32 v98, v99, v96
	v_fma_f32 v95, -v95, v98, v97
	v_div_fmas_f32 v95, v95, v96, v98
	v_div_scale_f32 v103, vcc, 1.0, v100, 1.0
	v_mul_f32_e32 v104, v103, v102
	v_fma_f32 v105, -v101, v104, v103
	v_fmac_f32_e32 v104, v105, v102
	v_fma_f32 v101, -v101, v104, v103
	v_div_fmas_f32 v101, v101, v102, v104
	v_div_scale_f32 v109, vcc, 1.0, v106, 1.0
	v_mul_f32_e32 v110, v109, v108
	v_fma_f32 v111, -v107, v110, v109
	v_fmac_f32_e32 v110, v111, v108
	v_fma_f32 v107, -v107, v110, v109
	v_div_fmas_f32 v107, v107, v108, v110
	v_div_fixup_f32 v89, v89, v88, 1.0
	v_div_fixup_f32 v95, v95, v94, 1.0
	v_div_fixup_f32 v101, v101, v100, 1.0
	v_div_fixup_f32 v107, v107, v106, 1.0
	v_mul_f32_e32 v89, v28, v89
	v_mul_f32_e32 v95, v29, v95
	v_mul_f32_e32 v101, v30, v101
	v_mul_f32_e32 v107, v31, v107
	v_mul_f32_e32 v89, v12, v89
	v_mul_f32_e32 v95, v13, v95
	v_mul_f32_e32 v101, v14, v101
	v_mul_f32_e32 v107, v15, v107
	v_cvt_pk_bf16_f32 v89, v89, v89
	v_cvt_pk_bf16_f32 v95, v95, v95
	v_cvt_pk_bf16_f32 v101, v101, v101
	v_cvt_pk_bf16_f32 v107, v107, v107
	ds_write_b16 v112, v89 offset:1536
	ds_write_b16 v112, v95 offset:1600
	ds_write_b16 v112, v101 offset:1664
	ds_write_b16 v112, v107 offset:1728
	ds_read_b128 v[120:123], v113
	ds_read_b128 v[124:127], v113 offset:1024
	s_waitcnt lgkmcnt(0)
	global_store_dwordx4 v114, v[120:123], s[98:99]
	s_add_u32 s98, s98, 0x16000
	s_addc_u32 s99, s99, 0
	global_store_dwordx4 v114, v[124:127], s[98:99]
	s_add_u32 s98, s98, 0x16000
	s_addc_u32 s99, s99, 0
	s_add_i32 s57, s57, s92
	s_cmpk_gt_i32 s57, 0x107f
	s_cbranch_scc1 .LBB0_1043

.LBB0_2283:
	v_lshl_or_b32 v115, v183, 3, v191
	v_lshrrev_b32_e32 v116, 6, v115
	v_and_b32_e32 v117, 63, v115
	v_lshlrev_b32_e32 v113, 11, v116
	v_add_u32_e32 v113, 0x10000, v113
	v_readfirstlane_b32 s100, v116
	v_and_b32_e32 v112, 31, v117
	v_lshl_add_u32 v112, v112, 1, v113
	v_lshrrev_b32_e32 v116, 5, v117
	v_lshl_add_u32 v112, v116, 8, v112
	v_lshl_add_u32 v113, v117, 4, v113
	v_lshrrev_b32_e32 v116, 2, v117
	v_mul_u32_u24_e32 v116, 0x1600, v116
	v_and_b32_e32 v114, 3, v117
	v_lshl_add_u32 v114, v114, 4, v116
	s_lshr_b32 s101, s100, 1
	s_lshl_b32 s101, s101, 6
	s_add_u32 s101, s101, s48
	s_mul_i32 s101, s101, 0x1600
	s_and_b32 s100, s100, 1
	s_lshl_b32 s100, s100, 6
	s_add_u32 s100, s100, s49
	s_add_u32 s101, s101, s100
	s_add_u32 s98, s90, 0x3971900
	s_addc_u32 s99, s91, 0
	s_add_u32 s98, s98, s101
	s_addc_u32 s99, s99, 0
	v_mul_f32_e32 v64, 0xbfb8aa3b, v48
	v_mul_f32_e32 v70, 0xbfb8aa3b, v49
	v_mul_f32_e32 v76, 0xbfb8aa3b, v50
	v_mul_f32_e32 v82, 0xbfb8aa3b, v51
	v_exp_f32_e32 v64, v64
	v_exp_f32_e32 v70, v70
	v_exp_f32_e32 v76, v76
	v_exp_f32_e32 v82, v82
	v_add_f32_e32 v64, 1.0, v64
	v_add_f32_e32 v70, 1.0, v70
	v_add_f32_e32 v76, 1.0, v76
	v_add_f32_e32 v82, 1.0, v82
	v_div_scale_f32 v65, s[4:5], v64, v64, 1.0
	v_div_scale_f32 v71, s[4:5], v70, v70, 1.0
	v_div_scale_f32 v77, s[4:5], v76, v76, 1.0
	v_div_scale_f32 v83, s[4:5], v82, v82, 1.0
	v_rcp_f32_e32 v66, v65
	v_rcp_f32_e32 v72, v71
	v_rcp_f32_e32 v78, v77
	v_rcp_f32_e32 v84, v83
	v_fma_f32 v69, -v65, v66, 1.0
	v_fma_f32 v75, -v71, v72, 1.0
	v_fma_f32 v81, -v77, v78, 1.0
	v_fma_f32 v87, -v83, v84, 1.0
	v_fmac_f32_e32 v66, v69, v66
	v_fmac_f32_e32 v72, v75, v72
	v_fmac_f32_e32 v78, v81, v78
	v_fmac_f32_e32 v84, v87, v84
	v_div_scale_f32 v67, vcc, 1.0, v64, 1.0
	v_mul_f32_e32 v88, 0xbfb8aa3b, v52
	v_mul_f32_e32 v68, v67, v66
	v_mul_f32_e32 v94, 0xbfb8aa3b, v53
	v_fma_f32 v69, -v65, v68, v67
	v_mul_f32_e32 v100, 0xbfb8aa3b, v54
	v_fmac_f32_e32 v68, v69, v66
	v_mul_f32_e32 v106, 0xbfb8aa3b, v55
	v_fma_f32 v65, -v65, v68, v67
	v_exp_f32_e32 v88, v88
	v_div_fmas_f32 v65, v65, v66, v68
	v_exp_f32_e32 v94, v94
	v_div_scale_f32 v73, vcc, 1.0, v70, 1.0
	v_exp_f32_e32 v100, v100
	v_mul_f32_e32 v74, v73, v72
	v_exp_f32_e32 v106, v106
	v_fma_f32 v75, -v71, v74, v73
	v_add_f32_e32 v88, 1.0, v88
	v_fmac_f32_e32 v74, v75, v72
	v_add_f32_e32 v94, 1.0, v94
	v_fma_f32 v71, -v71, v74, v73
	v_add_f32_e32 v100, 1.0, v100
	v_div_fmas_f32 v71, v71, v72, v74
	v_add_f32_e32 v106, 1.0, v106
	v_div_scale_f32 v79, vcc, 1.0, v76, 1.0
	v_div_scale_f32 v89, s[4:5], v88, v88, 1.0
	v_mul_f32_e32 v80, v79, v78
	v_div_scale_f32 v95, s[4:5], v94, v94, 1.0
	v_fma_f32 v81, -v77, v80, v79
	v_div_scale_f32 v101, s[4:5], v100, v100, 1.0
	v_fmac_f32_e32 v80, v81, v78
	v_div_scale_f32 v107, s[4:5], v106, v106, 1.0
	v_fma_f32 v77, -v77, v80, v79
	v_rcp_f32_e32 v90, v89
	v_div_fmas_f32 v77, v77, v78, v80
	v_rcp_f32_e32 v96, v95
	v_div_scale_f32 v85, vcc, 1.0, v82, 1.0
	v_rcp_f32_e32 v102, v101
	v_mul_f32_e32 v86, v85, v84
	v_rcp_f32_e32 v108, v107
	v_fma_f32 v87, -v83, v86, v85
	v_fma_f32 v93, -v89, v90, 1.0
	v_fmac_f32_e32 v86, v87, v84
	v_fma_f32 v99, -v95, v96, 1.0
	v_fma_f32 v83, -v83, v86, v85
	v_fma_f32 v105, -v101, v102, 1.0
	v_div_fmas_f32 v83, v83, v84, v86
	v_fma_f32 v111, -v107, v108, 1.0
	v_fmac_f32_e32 v90, v93, v90
	v_fmac_f32_e32 v96, v99, v96
	v_fmac_f32_e32 v102, v105, v102
	v_fmac_f32_e32 v108, v111, v108
	v_div_fixup_f32 v65, v65, v64, 1.0
	v_div_fixup_f32 v71, v71, v70, 1.0
	v_div_fixup_f32 v77, v77, v76, 1.0
	v_div_fixup_f32 v83, v83, v82, 1.0
	v_mul_f32_e32 v65, v48, v65
	v_mul_f32_e32 v71, v49, v71
	v_mul_f32_e32 v77, v50, v77
	v_mul_f32_e32 v83, v51, v83
	v_mul_f32_e32 v65, v32, v65
	v_mul_f32_e32 v71, v33, v71
	v_mul_f32_e32 v77, v34, v77
	v_mul_f32_e32 v83, v35, v83
	v_cvt_pk_bf16_f32 v65, v65, v65
	v_cvt_pk_bf16_f32 v71, v71, v71
	v_cvt_pk_bf16_f32 v77, v77, v77
	v_cvt_pk_bf16_f32 v83, v83, v83
	ds_write_b16 v112, v65
	ds_write_b16 v112, v71 offset:64
	ds_write_b16 v112, v77 offset:128
	ds_write_b16 v112, v83 offset:192
	v_div_scale_f32 v91, vcc, 1.0, v88, 1.0
	v_mul_f32_e32 v64, 0xbfb8aa3b, v56
	v_mul_f32_e32 v92, v91, v90
	v_mul_f32_e32 v70, 0xbfb8aa3b, v57
	v_fma_f32 v93, -v89, v92, v91
	v_mul_f32_e32 v76, 0xbfb8aa3b, v58
	v_fmac_f32_e32 v92, v93, v90
	v_mul_f32_e32 v82, 0xbfb8aa3b, v59
	v_fma_f32 v89, -v89, v92, v91
	v_exp_f32_e32 v64, v64
	v_div_fmas_f32 v89, v89, v90, v92
	v_exp_f32_e32 v70, v70
	v_div_scale_f32 v97, vcc, 1.0, v94, 1.0
	v_exp_f32_e32 v76, v76
	v_mul_f32_e32 v98, v97, v96
	v_exp_f32_e32 v82, v82
	v_fma_f32 v99, -v95, v98, v97
	v_add_f32_e32 v64, 1.0, v64
	v_fmac_f32_e32 v98, v99, v96
	v_add_f32_e32 v70, 1.0, v70
	v_fma_f32 v95, -v95, v98, v97
	v_add_f32_e32 v76, 1.0, v76
	v_div_fmas_f32 v95, v95, v96, v98
	v_add_f32_e32 v82, 1.0, v82
	v_div_scale_f32 v103, vcc, 1.0, v100, 1.0
	v_div_scale_f32 v65, s[4:5], v64, v64, 1.0
	v_mul_f32_e32 v104, v103, v102
	v_div_scale_f32 v71, s[4:5], v70, v70, 1.0
	v_fma_f32 v105, -v101, v104, v103
	v_div_scale_f32 v77, s[4:5], v76, v76, 1.0
	v_fmac_f32_e32 v104, v105, v102
	v_div_scale_f32 v83, s[4:5], v82, v82, 1.0
	v_fma_f32 v101, -v101, v104, v103
	v_rcp_f32_e32 v66, v65
	v_div_fmas_f32 v101, v101, v102, v104
	v_rcp_f32_e32 v72, v71
	v_div_scale_f32 v109, vcc, 1.0, v106, 1.0
	v_rcp_f32_e32 v78, v77
	v_mul_f32_e32 v110, v109, v108
	v_rcp_f32_e32 v84, v83
	v_fma_f32 v111, -v107, v110, v109
	v_fma_f32 v69, -v65, v66, 1.0
	v_fmac_f32_e32 v110, v111, v108
	v_fma_f32 v75, -v71, v72, 1.0
	v_fma_f32 v107, -v107, v110, v109
	v_fma_f32 v81, -v77, v78, 1.0
	v_div_fmas_f32 v107, v107, v108, v110
	v_fma_f32 v87, -v83, v84, 1.0
	v_fmac_f32_e32 v66, v69, v66
	v_fmac_f32_e32 v72, v75, v72
	v_fmac_f32_e32 v78, v81, v78
	v_fmac_f32_e32 v84, v87, v84
	v_div_fixup_f32 v89, v89, v88, 1.0
	v_div_fixup_f32 v95, v95, v94, 1.0
	v_div_fixup_f32 v101, v101, v100, 1.0
	v_div_fixup_f32 v107, v107, v106, 1.0
	v_mul_f32_e32 v89, v52, v89
	v_mul_f32_e32 v95, v53, v95
	v_mul_f32_e32 v101, v54, v101
	v_mul_f32_e32 v107, v55, v107
	v_mul_f32_e32 v89, v36, v89
	v_mul_f32_e32 v95, v37, v95
	v_mul_f32_e32 v101, v38, v101
	v_mul_f32_e32 v107, v39, v107
	v_cvt_pk_bf16_f32 v89, v89, v89
	v_cvt_pk_bf16_f32 v95, v95, v95
	v_cvt_pk_bf16_f32 v101, v101, v101
	v_cvt_pk_bf16_f32 v107, v107, v107
	ds_write_b16 v112, v89 offset:512
	ds_write_b16 v112, v95 offset:576
	ds_write_b16 v112, v101 offset:640
	ds_write_b16 v112, v107 offset:704
	v_div_scale_f32 v67, vcc, 1.0, v64, 1.0
	v_mul_f32_e32 v88, 0xbfb8aa3b, v60
	v_mul_f32_e32 v68, v67, v66
	v_mul_f32_e32 v94, 0xbfb8aa3b, v61
	v_fma_f32 v69, -v65, v68, v67
	v_mul_f32_e32 v100, 0xbfb8aa3b, v62
	v_fmac_f32_e32 v68, v69, v66
	v_mul_f32_e32 v106, 0xbfb8aa3b, v63
	v_fma_f32 v65, -v65, v68, v67
	v_exp_f32_e32 v88, v88
	v_div_fmas_f32 v65, v65, v66, v68
	v_exp_f32_e32 v94, v94
	v_div_scale_f32 v73, vcc, 1.0, v70, 1.0
	v_exp_f32_e32 v100, v100
	v_mul_f32_e32 v74, v73, v72
	v_exp_f32_e32 v106, v106
	v_fma_f32 v75, -v71, v74, v73
	v_add_f32_e32 v88, 1.0, v88
	v_fmac_f32_e32 v74, v75, v72
	v_add_f32_e32 v94, 1.0, v94
	v_fma_f32 v71, -v71, v74, v73
	v_add_f32_e32 v100, 1.0, v100
	v_div_fmas_f32 v71, v71, v72, v74
	v_add_f32_e32 v106, 1.0, v106
	v_div_scale_f32 v79, vcc, 1.0, v76, 1.0
	v_div_scale_f32 v89, s[4:5], v88, v88, 1.0
	v_mul_f32_e32 v80, v79, v78
	v_div_scale_f32 v95, s[4:5], v94, v94, 1.0
	v_fma_f32 v81, -v77, v80, v79
	v_div_scale_f32 v101, s[4:5], v100, v100, 1.0
	v_fmac_f32_e32 v80, v81, v78
	v_div_scale_f32 v107, s[4:5], v106, v106, 1.0
	v_fma_f32 v77, -v77, v80, v79
	v_rcp_f32_e32 v90, v89
	v_div_fmas_f32 v77, v77, v78, v80
	v_rcp_f32_e32 v96, v95
	v_div_scale_f32 v85, vcc, 1.0, v82, 1.0
	v_rcp_f32_e32 v102, v101
	v_mul_f32_e32 v86, v85, v84
	v_rcp_f32_e32 v108, v107
	v_fma_f32 v87, -v83, v86, v85
	v_fma_f32 v93, -v89, v90, 1.0
	v_fmac_f32_e32 v86, v87, v84
	v_fma_f32 v99, -v95, v96, 1.0
	v_fma_f32 v83, -v83, v86, v85
	v_fma_f32 v105, -v101, v102, 1.0
	v_div_fmas_f32 v83, v83, v84, v86
	v_fma_f32 v111, -v107, v108, 1.0
	v_fmac_f32_e32 v90, v93, v90
	v_fmac_f32_e32 v96, v99, v96
	v_fmac_f32_e32 v102, v105, v102
	v_fmac_f32_e32 v108, v111, v108
	v_div_fixup_f32 v65, v65, v64, 1.0
	v_div_fixup_f32 v71, v71, v70, 1.0
	v_div_fixup_f32 v77, v77, v76, 1.0
	v_div_fixup_f32 v83, v83, v82, 1.0
	v_mul_f32_e32 v65, v56, v65
	v_mul_f32_e32 v71, v57, v71
	v_mul_f32_e32 v77, v58, v77
	v_mul_f32_e32 v83, v59, v83
	v_mul_f32_e32 v65, v40, v65
	v_mul_f32_e32 v71, v41, v71
	v_mul_f32_e32 v77, v42, v77
	v_mul_f32_e32 v83, v43, v83
	v_cvt_pk_bf16_f32 v65, v65, v65
	v_cvt_pk_bf16_f32 v71, v71, v71
	v_cvt_pk_bf16_f32 v77, v77, v77
	v_cvt_pk_bf16_f32 v83, v83, v83
	ds_write_b16 v112, v65 offset:1024
	ds_write_b16 v112, v71 offset:1088
	ds_write_b16 v112, v77 offset:1152
	ds_write_b16 v112, v83 offset:1216
	v_div_scale_f32 v91, vcc, 1.0, v88, 1.0
	v_mul_f32_e32 v64, 0xbfb8aa3b, v16
	v_mul_f32_e32 v92, v91, v90
	v_mul_f32_e32 v70, 0xbfb8aa3b, v17
	v_fma_f32 v93, -v89, v92, v91
	v_mul_f32_e32 v76, 0xbfb8aa3b, v18
	v_fmac_f32_e32 v92, v93, v90
	v_mul_f32_e32 v82, 0xbfb8aa3b, v19
	v_fma_f32 v89, -v89, v92, v91
	v_exp_f32_e32 v64, v64
	v_div_fmas_f32 v89, v89, v90, v92
	v_exp_f32_e32 v70, v70
	v_div_scale_f32 v97, vcc, 1.0, v94, 1.0
	v_exp_f32_e32 v76, v76
	v_mul_f32_e32 v98, v97, v96
	v_exp_f32_e32 v82, v82
	v_fma_f32 v99, -v95, v98, v97
	v_add_f32_e32 v64, 1.0, v64
	v_fmac_f32_e32 v98, v99, v96
	v_add_f32_e32 v70, 1.0, v70
	v_fma_f32 v95, -v95, v98, v97
	v_add_f32_e32 v76, 1.0, v76
	v_div_fmas_f32 v95, v95, v96, v98
	v_add_f32_e32 v82, 1.0, v82
	v_div_scale_f32 v103, vcc, 1.0, v100, 1.0
	v_div_scale_f32 v65, s[4:5], v64, v64, 1.0
	v_mul_f32_e32 v104, v103, v102
	v_div_scale_f32 v71, s[4:5], v70, v70, 1.0
	v_fma_f32 v105, -v101, v104, v103
	v_div_scale_f32 v77, s[4:5], v76, v76, 1.0
	v_fmac_f32_e32 v104, v105, v102
	v_div_scale_f32 v83, s[4:5], v82, v82, 1.0
	v_fma_f32 v101, -v101, v104, v103
	v_rcp_f32_e32 v66, v65
	v_div_fmas_f32 v101, v101, v102, v104
	v_rcp_f32_e32 v72, v71
	v_div_scale_f32 v109, vcc, 1.0, v106, 1.0
	v_rcp_f32_e32 v78, v77
	v_mul_f32_e32 v110, v109, v108
	v_rcp_f32_e32 v84, v83
	v_fma_f32 v111, -v107, v110, v109
	v_fma_f32 v69, -v65, v66, 1.0
	v_fmac_f32_e32 v110, v111, v108
	v_fma_f32 v75, -v71, v72, 1.0
	v_fma_f32 v107, -v107, v110, v109
	v_fma_f32 v81, -v77, v78, 1.0
	v_div_fmas_f32 v107, v107, v108, v110
	v_fma_f32 v87, -v83, v84, 1.0
	v_fmac_f32_e32 v66, v69, v66
	v_fmac_f32_e32 v72, v75, v72
	v_fmac_f32_e32 v78, v81, v78
	v_fmac_f32_e32 v84, v87, v84
	v_div_fixup_f32 v89, v89, v88, 1.0
	v_div_fixup_f32 v95, v95, v94, 1.0
	v_div_fixup_f32 v101, v101, v100, 1.0
	v_div_fixup_f32 v107, v107, v106, 1.0
	v_mul_f32_e32 v89, v60, v89
	v_mul_f32_e32 v95, v61, v95
	v_mul_f32_e32 v101, v62, v101
	v_mul_f32_e32 v107, v63, v107
	v_mul_f32_e32 v89, v44, v89
	v_mul_f32_e32 v95, v45, v95
	v_mul_f32_e32 v101, v46, v101
	v_mul_f32_e32 v107, v47, v107
	v_cvt_pk_bf16_f32 v89, v89, v89
	v_cvt_pk_bf16_f32 v95, v95, v95
	v_cvt_pk_bf16_f32 v101, v101, v101
	v_cvt_pk_bf16_f32 v107, v107, v107
	ds_write_b16 v112, v89 offset:1536
	ds_write_b16 v112, v95 offset:1600
	ds_write_b16 v112, v101 offset:1664
	ds_write_b16 v112, v107 offset:1728
	ds_read_b128 v[120:123], v113
	ds_read_b128 v[124:127], v113 offset:1024
	v_div_scale_f32 v67, vcc, 1.0, v64, 1.0
	v_mul_f32_e32 v88, 0xbfb8aa3b, v20
	v_mul_f32_e32 v68, v67, v66
	v_mul_f32_e32 v94, 0xbfb8aa3b, v21
	v_fma_f32 v69, -v65, v68, v67
	v_mul_f32_e32 v100, 0xbfb8aa3b, v22
	v_fmac_f32_e32 v68, v69, v66
	v_mul_f32_e32 v106, 0xbfb8aa3b, v23
	v_fma_f32 v65, -v65, v68, v67
	v_exp_f32_e32 v88, v88
	v_div_fmas_f32 v65, v65, v66, v68
	v_exp_f32_e32 v94, v94
	v_div_scale_f32 v73, vcc, 1.0, v70, 1.0
	v_exp_f32_e32 v100, v100
	v_mul_f32_e32 v74, v73, v72
	v_exp_f32_e32 v106, v106
	v_fma_f32 v75, -v71, v74, v73
	v_add_f32_e32 v88, 1.0, v88
	v_fmac_f32_e32 v74, v75, v72
	v_add_f32_e32 v94, 1.0, v94
	v_fma_f32 v71, -v71, v74, v73
	v_add_f32_e32 v100, 1.0, v100
	v_div_fmas_f32 v71, v71, v72, v74
	v_add_f32_e32 v106, 1.0, v106
	v_div_scale_f32 v79, vcc, 1.0, v76, 1.0
	v_div_scale_f32 v89, s[4:5], v88, v88, 1.0
	v_mul_f32_e32 v80, v79, v78
	v_div_scale_f32 v95, s[4:5], v94, v94, 1.0
	v_fma_f32 v81, -v77, v80, v79
	v_div_scale_f32 v101, s[4:5], v100, v100, 1.0
	v_fmac_f32_e32 v80, v81, v78
	v_div_scale_f32 v107, s[4:5], v106, v106, 1.0
	v_fma_f32 v77, -v77, v80, v79
	v_rcp_f32_e32 v90, v89
	v_div_fmas_f32 v77, v77, v78, v80
	v_rcp_f32_e32 v96, v95
	v_div_scale_f32 v85, vcc, 1.0, v82, 1.0
	v_rcp_f32_e32 v102, v101
	v_mul_f32_e32 v86, v85, v84
	v_rcp_f32_e32 v108, v107
	v_fma_f32 v87, -v83, v86, v85
	v_fma_f32 v93, -v89, v90, 1.0
	v_fmac_f32_e32 v86, v87, v84
	v_fma_f32 v99, -v95, v96, 1.0
	v_fma_f32 v83, -v83, v86, v85
	v_fma_f32 v105, -v101, v102, 1.0
	v_div_fmas_f32 v83, v83, v84, v86
	v_fma_f32 v111, -v107, v108, 1.0
	v_fmac_f32_e32 v90, v93, v90
	v_fmac_f32_e32 v96, v99, v96
	v_fmac_f32_e32 v102, v105, v102
	v_fmac_f32_e32 v108, v111, v108
	s_waitcnt lgkmcnt(0)
	global_store_dwordx4 v114, v[120:123], s[98:99]
	s_add_u32 s98, s98, 0x16000
	s_addc_u32 s99, s99, 0
	global_store_dwordx4 v114, v[124:127], s[98:99]
	s_add_u32 s98, s98, 0x16000
	s_addc_u32 s99, s99, 0
	v_div_fixup_f32 v65, v65, v64, 1.0
	v_div_fixup_f32 v71, v71, v70, 1.0
	v_div_fixup_f32 v77, v77, v76, 1.0
	v_div_fixup_f32 v83, v83, v82, 1.0
	v_mul_f32_e32 v65, v16, v65
	v_mul_f32_e32 v71, v17, v71
	v_mul_f32_e32 v77, v18, v77
	v_mul_f32_e32 v83, v19, v83
	v_mul_f32_e32 v65, v0, v65
	v_mul_f32_e32 v71, v1, v71
	v_mul_f32_e32 v77, v2, v77
	v_mul_f32_e32 v83, v3, v83
	v_cvt_pk_bf16_f32 v65, v65, v65
	v_cvt_pk_bf16_f32 v71, v71, v71
	v_cvt_pk_bf16_f32 v77, v77, v77
	v_cvt_pk_bf16_f32 v83, v83, v83
	ds_write_b16 v112, v65
	ds_write_b16 v112, v71 offset:64
	ds_write_b16 v112, v77 offset:128
	ds_write_b16 v112, v83 offset:192
	v_div_scale_f32 v91, vcc, 1.0, v88, 1.0
	v_mul_f32_e32 v64, 0xbfb8aa3b, v24
	v_mul_f32_e32 v92, v91, v90
	v_mul_f32_e32 v70, 0xbfb8aa3b, v25
	v_fma_f32 v93, -v89, v92, v91
	v_mul_f32_e32 v76, 0xbfb8aa3b, v26
	v_fmac_f32_e32 v92, v93, v90
	v_mul_f32_e32 v82, 0xbfb8aa3b, v27
	v_fma_f32 v89, -v89, v92, v91
	v_exp_f32_e32 v64, v64
	v_div_fmas_f32 v89, v89, v90, v92
	v_exp_f32_e32 v70, v70
	v_div_scale_f32 v97, vcc, 1.0, v94, 1.0
	v_exp_f32_e32 v76, v76
	v_mul_f32_e32 v98, v97, v96
	v_exp_f32_e32 v82, v82
	v_fma_f32 v99, -v95, v98, v97
	v_add_f32_e32 v64, 1.0, v64
	v_fmac_f32_e32 v98, v99, v96
	v_add_f32_e32 v70, 1.0, v70
	v_fma_f32 v95, -v95, v98, v97
	v_add_f32_e32 v76, 1.0, v76
	v_div_fmas_f32 v95, v95, v96, v98
	v_add_f32_e32 v82, 1.0, v82
	v_div_scale_f32 v103, vcc, 1.0, v100, 1.0
	v_div_scale_f32 v65, s[4:5], v64, v64, 1.0
	v_mul_f32_e32 v104, v103, v102
	v_div_scale_f32 v71, s[4:5], v70, v70, 1.0
	v_fma_f32 v105, -v101, v104, v103
	v_div_scale_f32 v77, s[4:5], v76, v76, 1.0
	v_fmac_f32_e32 v104, v105, v102
	v_div_scale_f32 v83, s[4:5], v82, v82, 1.0
	v_fma_f32 v101, -v101, v104, v103
	v_rcp_f32_e32 v66, v65
	v_div_fmas_f32 v101, v101, v102, v104
	v_rcp_f32_e32 v72, v71
	v_div_scale_f32 v109, vcc, 1.0, v106, 1.0
	v_rcp_f32_e32 v78, v77
	v_mul_f32_e32 v110, v109, v108
	v_rcp_f32_e32 v84, v83
	v_fma_f32 v111, -v107, v110, v109
	v_fma_f32 v69, -v65, v66, 1.0
	v_fmac_f32_e32 v110, v111, v108
	v_fma_f32 v75, -v71, v72, 1.0
	v_fma_f32 v107, -v107, v110, v109
	v_fma_f32 v81, -v77, v78, 1.0
	v_div_fmas_f32 v107, v107, v108, v110
	v_fma_f32 v87, -v83, v84, 1.0
	v_fmac_f32_e32 v66, v69, v66
	v_fmac_f32_e32 v72, v75, v72
	v_fmac_f32_e32 v78, v81, v78
	v_fmac_f32_e32 v84, v87, v84
	v_div_fixup_f32 v89, v89, v88, 1.0
	v_div_fixup_f32 v95, v95, v94, 1.0
	v_div_fixup_f32 v101, v101, v100, 1.0
	v_div_fixup_f32 v107, v107, v106, 1.0
	v_mul_f32_e32 v89, v20, v89
	v_mul_f32_e32 v95, v21, v95
	v_mul_f32_e32 v101, v22, v101
	v_mul_f32_e32 v107, v23, v107
	v_mul_f32_e32 v89, v4, v89
	v_mul_f32_e32 v95, v5, v95
	v_mul_f32_e32 v101, v6, v101
	v_mul_f32_e32 v107, v7, v107
	v_cvt_pk_bf16_f32 v89, v89, v89
	v_cvt_pk_bf16_f32 v95, v95, v95
	v_cvt_pk_bf16_f32 v101, v101, v101
	v_cvt_pk_bf16_f32 v107, v107, v107
	ds_write_b16 v112, v89 offset:512
	ds_write_b16 v112, v95 offset:576
	ds_write_b16 v112, v101 offset:640
	ds_write_b16 v112, v107 offset:704
	v_div_scale_f32 v67, vcc, 1.0, v64, 1.0
	v_mul_f32_e32 v88, 0xbfb8aa3b, v28
	v_mul_f32_e32 v68, v67, v66
	v_mul_f32_e32 v94, 0xbfb8aa3b, v29
	v_fma_f32 v69, -v65, v68, v67
	v_mul_f32_e32 v100, 0xbfb8aa3b, v30
	v_fmac_f32_e32 v68, v69, v66
	v_mul_f32_e32 v106, 0xbfb8aa3b, v31
	v_fma_f32 v65, -v65, v68, v67
	v_exp_f32_e32 v88, v88
	v_div_fmas_f32 v65, v65, v66, v68
	v_exp_f32_e32 v94, v94
	v_div_scale_f32 v73, vcc, 1.0, v70, 1.0
	v_exp_f32_e32 v100, v100
	v_mul_f32_e32 v74, v73, v72
	v_exp_f32_e32 v106, v106
	v_fma_f32 v75, -v71, v74, v73
	v_add_f32_e32 v88, 1.0, v88
	v_fmac_f32_e32 v74, v75, v72
	v_add_f32_e32 v94, 1.0, v94
	v_fma_f32 v71, -v71, v74, v73
	v_add_f32_e32 v100, 1.0, v100
	v_div_fmas_f32 v71, v71, v72, v74
	v_add_f32_e32 v106, 1.0, v106
	v_div_scale_f32 v79, vcc, 1.0, v76, 1.0
	v_div_scale_f32 v89, s[4:5], v88, v88, 1.0
	v_mul_f32_e32 v80, v79, v78
	v_div_scale_f32 v95, s[4:5], v94, v94, 1.0
	v_fma_f32 v81, -v77, v80, v79
	v_div_scale_f32 v101, s[4:5], v100, v100, 1.0
	v_fmac_f32_e32 v80, v81, v78
	v_div_scale_f32 v107, s[4:5], v106, v106, 1.0
	v_fma_f32 v77, -v77, v80, v79
	v_rcp_f32_e32 v90, v89
	v_div_fmas_f32 v77, v77, v78, v80
	v_rcp_f32_e32 v96, v95
	v_div_scale_f32 v85, vcc, 1.0, v82, 1.0
	v_rcp_f32_e32 v102, v101
	v_mul_f32_e32 v86, v85, v84
	v_rcp_f32_e32 v108, v107
	v_fma_f32 v87, -v83, v86, v85
	v_fma_f32 v93, -v89, v90, 1.0
	v_fmac_f32_e32 v86, v87, v84
	v_fma_f32 v99, -v95, v96, 1.0
	v_fma_f32 v83, -v83, v86, v85
	v_fma_f32 v105, -v101, v102, 1.0
	v_div_fmas_f32 v83, v83, v84, v86
	v_fma_f32 v111, -v107, v108, 1.0
	v_fmac_f32_e32 v90, v93, v90
	v_fmac_f32_e32 v96, v99, v96
	v_fmac_f32_e32 v102, v105, v102
	v_fmac_f32_e32 v108, v111, v108
	v_div_fixup_f32 v65, v65, v64, 1.0
	v_div_fixup_f32 v71, v71, v70, 1.0
	v_div_fixup_f32 v77, v77, v76, 1.0
	v_div_fixup_f32 v83, v83, v82, 1.0
	v_mul_f32_e32 v65, v24, v65
	v_mul_f32_e32 v71, v25, v71
	v_mul_f32_e32 v77, v26, v77
	v_mul_f32_e32 v83, v27, v83
	v_mul_f32_e32 v65, v8, v65
	v_mul_f32_e32 v71, v9, v71
	v_mul_f32_e32 v77, v10, v77
	v_mul_f32_e32 v83, v11, v83
	v_cvt_pk_bf16_f32 v65, v65, v65
	v_cvt_pk_bf16_f32 v71, v71, v71
	v_cvt_pk_bf16_f32 v77, v77, v77
	v_cvt_pk_bf16_f32 v83, v83, v83
	ds_write_b16 v112, v65 offset:1024
	ds_write_b16 v112, v71 offset:1088
	ds_write_b16 v112, v77 offset:1152
	ds_write_b16 v112, v83 offset:1216
	v_div_scale_f32 v91, vcc, 1.0, v88, 1.0
	v_mul_f32_e32 v92, v91, v90
	v_fma_f32 v93, -v89, v92, v91
	v_fmac_f32_e32 v92, v93, v90
	v_fma_f32 v89, -v89, v92, v91
	v_div_fmas_f32 v89, v89, v90, v92
	v_div_scale_f32 v97, vcc, 1.0, v94, 1.0
	v_mul_f32_e32 v98, v97, v96
	v_fma_f32 v99, -v95, v98, v97
	v_fmac_f32_e32 v98, v99, v96
	v_fma_f32 v95, -v95, v98, v97
	v_div_fmas_f32 v95, v95, v96, v98
	v_div_scale_f32 v103, vcc, 1.0, v100, 1.0
	v_mul_f32_e32 v104, v103, v102
	v_fma_f32 v105, -v101, v104, v103
	v_fmac_f32_e32 v104, v105, v102
	v_fma_f32 v101, -v101, v104, v103
	v_div_fmas_f32 v101, v101, v102, v104
	v_div_scale_f32 v109, vcc, 1.0, v106, 1.0
	v_mul_f32_e32 v110, v109, v108
	v_fma_f32 v111, -v107, v110, v109
	v_fmac_f32_e32 v110, v111, v108
	v_fma_f32 v107, -v107, v110, v109
	v_div_fmas_f32 v107, v107, v108, v110
	v_div_fixup_f32 v89, v89, v88, 1.0
	v_div_fixup_f32 v95, v95, v94, 1.0
	v_div_fixup_f32 v101, v101, v100, 1.0
	v_div_fixup_f32 v107, v107, v106, 1.0
	v_mul_f32_e32 v89, v28, v89
	v_mul_f32_e32 v95, v29, v95
	v_mul_f32_e32 v101, v30, v101
	v_mul_f32_e32 v107, v31, v107
	v_mul_f32_e32 v89, v12, v89
	v_mul_f32_e32 v95, v13, v95
	v_mul_f32_e32 v101, v14, v101
	v_mul_f32_e32 v107, v15, v107
	v_cvt_pk_bf16_f32 v89, v89, v89
	v_cvt_pk_bf16_f32 v95, v95, v95
	v_cvt_pk_bf16_f32 v101, v101, v101
	v_cvt_pk_bf16_f32 v107, v107, v107
	ds_write_b16 v112, v89 offset:1536
	ds_write_b16 v112, v95 offset:1600
	ds_write_b16 v112, v101 offset:1664
	ds_write_b16 v112, v107 offset:1728
	ds_read_b128 v[120:123], v113
	ds_read_b128 v[124:127], v113 offset:1024
	s_waitcnt lgkmcnt(0)
	global_store_dwordx4 v114, v[120:123], s[98:99]
	s_add_u32 s98, s98, 0x16000
	s_addc_u32 s99, s99, 0
	global_store_dwordx4 v114, v[124:127], s[98:99]
	s_add_u32 s98, s98, 0x16000
	s_addc_u32 s99, s99, 0
	s_add_i32 s47, s47, s92
	s_cmpk_gt_i32 s47, 0x107f
	s_cbranch_scc1 .LBB0_2292
